# speedup vs baseline: 1.0132x; 1.0132x over previous
; __global__ __launch_bounds__(512, 2) void mega(Params p_unused, int ph_lo, int ph_hi) {
;     ...
;         for (int i = 0; i < ng; ++i) {
;             GemmD g; g.M = MT; g.bias = nullptr; g.g = nullptr; g.xf = p->out; g.x0p = p->out; g.x0s = p->out + (size_t)MP * DM; g.ob = nullptr; g.ob2 = nullptr; g.ldc = 0; g.gs = (const bf16_t*)(p->ws + WS_GS); g.vc0 = 0; g.split = 0; g.part = (float*)(p->ws + WS_PART); g.A = U; g.Bt = WB; g.N = 2048; g.K = 2048; g.mode = E_ACC;
;             switch (s) {
;             case 1: g.Bt = WB + WB_IN; g.N = NINP; g.mode = E_BF16; g.ob = Pb; g.ldc = NINP; break;
;             case 3: g.A = U + (size_t)MP * DM; g.M = MS; g.Bt = WB + WB_GATE; g.N = 6144; g.mode = E_GATES; g.ob = (bf16_t*)(p->ws + WS_GS); g.ldc = 6144; g.bias = p->in[13] + (size_t)layer * 6144;
;                     if ((int)gridDim.x >= 256) g.vc0 = 192; break;
;             case 4: g.M = MP; g.Bt = WB + WB_GATE; g.N = 6144; g.mode = E_GATES; g.ob = Pb; g.ldc = 6144; g.bias = p->in[13] + (size_t)layer * 6144; break;
;             case 5: g.A = BR + (size_t)i * MT * 1024; g.Bt = WB + WB_BO + (size_t)i * 2048 * 1024; g.K = 1024; g.mode = E_MERGE0 + i; g.g = Pb; g.xf = MG; g.ob2 = U; if ((int)gridDim.x >= 64) g.split = -1; break;
;             case 6: g.Bt = WB + WB_OUT; g.mode = E_RESID; g.x0p = xp; g.x0s = xs; g.split = KSPLIT; break;
;             case 8: if (i == 0) { g.Bt = WB + WB_GU; g.N = 2 * DFF; g.mode = E_SWIGLU; g.ob = Pb; g.ldc = DFF; }
;                     else { g.A = PE; g.Bt = WB + WB_PP; g.K = 256; g.mode = E_BF16; g.ob = PP; g.ldc = 2048;
;                            const int rem = (MT / BM) * (2 * DFF / BM) % (int)gridDim.x; if (rem > 0 && (int)gridDim.x - rem >= 64) g.vc0 = rem; }
;                     break;
;             case 9: g.A = Pb; g.Bt = WB + WB_DOWN; g.K = DFF; g.mode = E_ACC; g.split = KSPLIT; break;
;             default: g.Bt = WB + WB_PG; g.mode = E_PLE; g.g = PP; g.split = KSPLIT; break;
;             }
;             gemm_phase(lds, g);
.LBB0_59:
	s_setprio 0
	s_movk_i32 s87, 0xffe0
	s_movk_i32 s58, 0x3ff
	s_movk_i32 s59, 0x410
	v_readlane_b32 s22, v254, 51
	s_barrier

; __device__ __forceinline__ int bid_() { int b = blockIdx.x; asm volatile("" : "+s"(b)); return b; }
; #define PG8_STAGE(bufoff, gbase, voff) do { _Pragma("unroll") for (int _i = 0; _i < 2; ++_i) \
;         __builtin_amdgcn_global_load_lds((const unsigned*)((const char*)(gbase) + (voff)[_i]), (LAS unsigned*)(lds + (bufoff) + ldsw + _i * 8192), 16, 0, 0); } while (0)
; #define PG8_BAR __builtin_amdgcn_s_barrier()
; __device__ __forceinline__ void gemm_phase(LAS unsigned char* lds, const GemmD& g) {
;     int tid_ = threadIdx.x; asm volatile("" : "+v"(tid_)); const int tid = tid_, wid = __builtin_amdgcn_readfirstlane(tid >> 6), lane = tid & 63, wr = wid >> 2, wc = wid & 3, fr = lane & 15, fq = lane >> 4;
;     const int K = g.K;
;     const bool perm = (g.mode == E_BF16 || g.mode == E_GATES || g.mode == E_SWIGLU);
;     const int nM = g.M / BM, nN = g.N / BM, G = (int)gridDim.x - g.vc0, cblk = bid_() - g.vc0;
;     if (cblk < 0) return;
;     unsigned voffA[2], voffB[2];
; #pragma unroll
;     for (int i = 0; i < 2; ++i) { int R, C; stage_rc(tid * 16 + i * 8192, R, C); const int Rb = perm ? ((R & ~31) + perm32(R & 31)) : R;
;         voffA[i] = (unsigned)(R * K + C) * 2u; voffB[i] = (unsigned)(Rb * K + C) * 2u; }
;     const size_t kstep = (size_t)(BK * 2);
;     const size_t hstep = (size_t)HALF * K * 2;
;     const size_t tstep = 2 * hstep;
;     const unsigned ldsw = (unsigned)wid * 1024u;
;     const int aoff = lds_byte(wr * 64 + fr, fq * 8), boff = lds_byte(wc * 32 + fr, fq * 8);
;     ...
;     Unit cur, nxt; int ui = 0;
;     if (!unit_get(g, nM, nN, G, cblk, 0, cur)) return;
;     f32x4 acc[2][2][4][2];
; #pragma unroll
;     for (int a = 0; a < 2; ++a)
; #pragma unroll
;         for (int b = 0; b < 2; ++b)
; #pragma unroll
;             for (int m = 0; m < 4; ++m)
; #pragma unroll
;                 for (int n = 0; n < 2; ++n) acc[a][b][m][n] = (f32x4){0.f, 0.f, 0.f, 0.f};
;     bf16x8 At[4][2], B0[2][2], B1[2][2];
;     const char* cA = (const char*)g.A + (size_t)cur.pm * tstep + (size_t)cur.k0 * kstep; const char* cB = (const char*)g.Bt + (size_t)cur.pn * tstep + (size_t)cur.k0 * kstep;
;     PG8_STAGE(PG8_SB(0, 0), cB, voffB); PG8_STAGE(PG8_SA(0, 0), cA, voffA); PG8_STAGE(PG8_SB(0, 1), cB + hstep, voffB); PG8_STAGE(PG8_SA(0, 1), cA + hstep, voffA);
;     if (wr == 1) PG8_BAR;
.LBB0_123:
	s_and_b64 vcc, exec, s[2:3]
	s_cbranch_vccz .LBB0_60
	v_lshlrev_b32_e32 v13, 6, v13
	v_sub_u32_e32 v12, v12, v13
	v_lshlrev_b32_e32 v10, 5, v10
	v_ashrrev_i16_sdwa v12, v213, sext(v12) dst_sel:DWORD dst_unused:UNUSED_PAD src0_sel:DWORD src1_sel:BYTE_0
	v_and_b32_e32 v10, 32, v10
	v_bfe_i32 v12, v12, 0, 16
	v_add_u32_e32 v13, v10, v12
	v_mul_lo_u32 v11, v11, s0
	v_mul_lo_u32 v14, v14, s0
	v_lshlrev_b32_e32 v2, 5, v2
	v_add_lshl_u32 v166, v13, v11, 1
	v_add_lshl_u32 v168, v14, v13, 1
	v_and_b32_e32 v13, 32, v2
	v_lshlrev_b32_e32 v2, 6, v7
	v_sub_u32_e32 v2, v3, v2
	v_ashrrev_i16_sdwa v2, v213, sext(v2) dst_sel:DWORD dst_unused:UNUSED_PAD src0_sel:DWORD src1_sel:BYTE_0
	s_mov_b32 s1, s34
	v_bfe_i32 v14, v2, 0, 16
	s_lshl_b64 s[72:73], s[0:1], 8
	s_lshl_b64 s[58:59], s[0:1], 9
	v_add_u32_e32 v2, v13, v14
	v_mul_lo_u32 v15, v6, s0
	v_mul_lo_u32 v3, v9, s0
	s_ashr_i32 s1, s56, 31
	v_add_lshl_u32 v170, v2, v15, 1
	v_add_lshl_u32 v172, v3, v2, 1
	s_mul_i32 s1, s58, s1
	s_mul_hi_u32 s2, s58, s56
	v_ashrrev_i32_e32 v2, 31, v1
	s_add_i32 s1, s2, s1
	s_lshr_b32 s2, s0, 23
	v_mul_lo_u32 v2, s58, v2
	v_mul_hi_u32 v3, s58, v1
	s_ashr_i32 s6, s33, 6
	s_mul_i32 s0, s2, s56
	v_add_u32_e32 v2, v3, v2
	v_mul_lo_u32 v3, s2, v1
	s_ashr_i32 s7, s33, 8
	s_lshl_b32 s87, s6, 10
	s_add_i32 s1, s1, s0
	s_mul_i32 s0, s58, s56
	v_add_u32_e32 v3, v2, v3
	v_mul_lo_u32 v2, s58, v1
	s_add_u32 s0, s18, s0
	v_lshl_add_u64 v[2:3], s[92:93], 0, v[2:3]
	s_addc_u32 s1, s19, s1
	v_lshl_add_u64 v[2:3], v[2:3], 0, v[4:5]
	s_add_i32 s2, s87, 0
	s_add_i32 m0, s2, 0x10000
	v_readfirstlane_b32 s8, v2
	v_readfirstlane_b32 s9, v3
	v_lshl_add_u64 v[4:5], s[0:1], 0, v[4:5]
	s_add_i32 s3, s2, 0x2000
	v_readfirstlane_b32 s0, v4
	v_readfirstlane_b32 s1, v5
	v_lshl_add_u64 v[6:7], v[2:3], 0, s[72:73]
	global_load_lds_dwordx4 v172, s[8:9]
	s_add_i32 m0, s2, 0x12000
	v_lshl_add_u64 v[16:17], v[4:5], 0, s[72:73]
	global_load_lds_dwordx4 v168, s[8:9]
	s_mov_b32 m0, s2
	s_add_i32 s64, s2, 0x4000
	global_load_lds_dwordx4 v170, s[0:1]
	s_mov_b32 m0, s3
	s_add_i32 s65, s2, 0x6000
	global_load_lds_dwordx4 v166, s[0:1]
	s_add_i32 m0, s2, 0x14000
	v_readfirstlane_b32 s0, v6
	v_readfirstlane_b32 s1, v7
	v_writelane_b32 v255, s28, 27
	s_nop 1
	v_writelane_b32 v255, s29, 28
	v_writelane_b32 v255, s33, 29
	global_load_lds_dwordx4 v172, s[0:1]
	s_add_i32 m0, s2, 0x16000
	s_cmp_lg_u32 s7, 1
	global_load_lds_dwordx4 v168, s[0:1]
	v_readfirstlane_b32 s0, v16
	v_readfirstlane_b32 s1, v17
	s_mov_b32 m0, s64
	s_nop 3
	global_load_lds_dwordx4 v170, s[0:1]
	s_mov_b32 m0, s65
	s_nop 0
	global_load_lds_dwordx4 v166, s[0:1]
	s_cbranch_scc1 .LBB0_126
	s_setprio 1
	s_barrier

; #define PG8_STAGE(bufoff, gbase, voff) do { _Pragma("unroll") for (int _i = 0; _i < 2; ++_i) \
;         __builtin_amdgcn_global_load_lds((const unsigned*)((const char*)(gbase) + (voff)[_i]), (LAS unsigned*)(lds + (bufoff) + ldsw + _i * 8192), 16, 0, 0); } while (0)
; #define PG8_LDA(dst, b, h) do { _Pragma("unroll") for (int m = 0; m < 4; ++m) _Pragma("unroll") for (int k = 0; k < 2; ++k) dst[m][k] = *(const LAS bf16x8*)(lds + PG8_SA(b, h) + aoff + m * 2048 + k * 1024); } while (0)
; #define PG8_LDB(dst, b, h) do { _Pragma("unroll") for (int n = 0; n < 2; ++n) _Pragma("unroll") for (int k = 0; k < 2; ++k) dst[n][k] = *(const LAS bf16x8*)(lds + PG8_SB(b, h) + boff + n * 2048 + k * 1024); } while (0)
; #define PG8_MMA(ai, bj, At, Bt) do { __builtin_amdgcn_s_setprio(1); _Pragma("unroll") for (int m = 0; m < 4; ++m) _Pragma("unroll") for (int n = 0; n < 2; ++n) _Pragma("unroll") for (int k = 0; k < 2; ++k) \
;         acc[ai][bj][m][n] = __builtin_amdgcn_mfma_f32_16x16x32_bf16(Bt[n][k], At[m][k], acc[ai][bj][m][n], 0, 0, 0); __builtin_amdgcn_s_setprio(0); } while (0)
; #define PG8_WAIT_L(n) asm volatile("s_waitcnt lgkmcnt(" #n ")" ::: "memory")
; #define PG8_BAR __builtin_amdgcn_s_barrier()
; #define PG8_SCHED __builtin_amdgcn_sched_barrier(0)
; __device__ __forceinline__ void gemm_phase(LAS unsigned char* lds, const GemmD& g) {
;     ...
;             PG8_LDB(B0, 0, 0); PG8_SCHED; PG8_LDA(At, 0, 0); PG8_STAGE(PG8_SA(1, 1), a1 + hstep, voffA);
;             PG8_WAIT_L(8); PG8_BAR; PG8_WAIT_L(0); PG8_MMA(0, 0, At, B0); PG8_BAR; PG8_SCHED;
;             PG8_LDB(B1, 0, 1); PG8_STAGE(PG8_SB(0, 0), b2, voffB);
;             PG8_BAR; PG8_WAIT_L(0); PG8_MMA(0, 1, At, B1); PG8_BAR;
;             PG8_LDA(At, 0, 1); PG8_STAGE(PG8_SA(0, 0), a2, voffA);
;             PG8_BAR; PG8_WAIT_L(0); PG8_MMA(1, 0, At, B0); PG8_BAR; PG8_SCHED;
.LBB0_145:
	s_add_i32 s6, 0, 0x10000
	v_add_u32_e32 v148, s6, v229
	ds_read_b128 v[136:139], v148
	ds_read_b128 v[140:143], v148 offset:1024
	ds_read_b128 v[144:147], v148 offset:2048
	ds_read_b128 v[148:151], v148 offset:3072
	v_lshl_add_u64 v[152:153], v[130:131], 0, s[44:45]
	v_cmp_eq_u32_e32 vcc, s4, v135
	s_add_i32 s5, s4, 2
	s_nop 0
	v_cndmask_b32_e32 v165, v153, v181, vcc
	v_cndmask_b32_e32 v164, v152, v180, vcc
	v_cndmask_b32_e32 v243, v133, v183, vcc
	v_cndmask_b32_e32 v242, v132, v182, vcc
	v_lshl_add_u64 v[204:205], v[130:131], 0, v[174:175]
	s_add_i32 m0, s2, 0xc000
	ds_read_b128 v[152:155], v233
	ds_read_b128 v[156:159], v233 offset:1024
	ds_read_b128 v[160:163], v233 offset:2048
	ds_read_b128 v[184:187], v233 offset:3072
	ds_read_b128 v[188:191], v233 offset:4096
	ds_read_b128 v[192:195], v233 offset:5120
	ds_read_b128 v[196:199], v233 offset:6144
	ds_read_b128 v[200:203], v233 offset:7168
	global_load_lds_dwordx4 v[204:205], off
	v_lshl_add_u64 v[204:205], v[130:131], 0, v[176:177]
	s_add_i32 m0, s2, 0xe000
	s_nop 0
	global_load_lds_dwordx4 v[204:205], off
	s_waitcnt lgkmcnt(8)
	s_barrier
	s_waitcnt lgkmcnt(0)
	s_waitcnt lgkmcnt(0)
	v_mfma_f32_16x16x32_bf16 v[126:129], v[136:139], v[152:155], v[126:129]
	v_mfma_f32_16x16x32_bf16 v[122:125], v[144:147], v[152:155], v[122:125]
	v_mfma_f32_16x16x32_bf16 v[110:113], v[136:139], v[160:163], v[110:113]
	v_mfma_f32_16x16x32_bf16 v[106:109], v[144:147], v[160:163], v[106:109]
	v_mfma_f32_16x16x32_bf16 v[94:97], v[136:139], v[188:191], v[94:97]
	v_mfma_f32_16x16x32_bf16 v[90:93], v[144:147], v[188:191], v[90:93]
	v_mfma_f32_16x16x32_bf16 v[78:81], v[136:139], v[196:199], v[78:81]
	v_mfma_f32_16x16x32_bf16 v[74:77], v[144:147], v[196:199], v[74:77]
	v_mfma_f32_16x16x32_bf16 v[126:129], v[140:143], v[156:159], v[126:129]
	v_mfma_f32_16x16x32_bf16 v[122:125], v[148:151], v[156:159], v[122:125]
	v_mfma_f32_16x16x32_bf16 v[110:113], v[140:143], v[184:187], v[110:113]
	v_mfma_f32_16x16x32_bf16 v[106:109], v[148:151], v[184:187], v[106:109]
	v_mfma_f32_16x16x32_bf16 v[94:97], v[140:143], v[192:195], v[94:97]
	v_mfma_f32_16x16x32_bf16 v[90:93], v[148:151], v[192:195], v[90:93]
	v_mfma_f32_16x16x32_bf16 v[78:81], v[140:143], v[200:203], v[78:81]
	v_mfma_f32_16x16x32_bf16 v[74:77], v[148:151], v[200:203], v[74:77]
	s_barrier
	s_add_i32 s4, 0, 0x14000
	s_add_i32 s6, s6, s87
	v_add_u32_e32 v238, s4, v229
	v_lshl_add_u64 v[244:245], v[242:243], 0, v[172:173]
	s_mov_b32 m0, s6
	ds_read_b128 v[204:207], v238
	ds_read_b128 v[208:211], v238 offset:1024
	ds_read_b128 v[234:237], v238 offset:2048
	ds_read_b128 v[238:241], v238 offset:3072
	global_load_lds_dwordx4 v[244:245], off
	v_lshl_add_u64 v[246:247], v[242:243], 0, v[168:169]
	s_add_i32 m0, s6, 0x2000
	s_nop 0
	global_load_lds_dwordx4 v[246:247], off
	s_barrier
	s_waitcnt lgkmcnt(0)
	s_waitcnt lgkmcnt(0)
	v_mfma_f32_16x16x32_bf16 v[118:121], v[204:207], v[152:155], v[118:121]
	v_mfma_f32_16x16x32_bf16 v[114:117], v[234:237], v[152:155], v[114:117]
	v_mfma_f32_16x16x32_bf16 v[102:105], v[204:207], v[160:163], v[102:105]
	v_mfma_f32_16x16x32_bf16 v[98:101], v[234:237], v[160:163], v[98:101]
	v_mfma_f32_16x16x32_bf16 v[86:89], v[204:207], v[188:191], v[86:89]
	v_mfma_f32_16x16x32_bf16 v[82:85], v[234:237], v[188:191], v[82:85]
	v_mfma_f32_16x16x32_bf16 v[70:73], v[204:207], v[196:199], v[70:73]
	v_mfma_f32_16x16x32_bf16 v[66:69], v[234:237], v[196:199], v[66:69]
	v_mfma_f32_16x16x32_bf16 v[118:121], v[208:211], v[156:159], v[118:121]
	v_mfma_f32_16x16x32_bf16 v[114:117], v[238:241], v[156:159], v[114:117]
	v_mfma_f32_16x16x32_bf16 v[102:105], v[208:211], v[184:187], v[102:105]
	v_mfma_f32_16x16x32_bf16 v[98:101], v[238:241], v[184:187], v[98:101]
	v_mfma_f32_16x16x32_bf16 v[86:89], v[208:211], v[192:195], v[86:89]
	v_mfma_f32_16x16x32_bf16 v[82:85], v[238:241], v[192:195], v[82:85]
	v_mfma_f32_16x16x32_bf16 v[70:73], v[208:211], v[200:203], v[70:73]
	v_mfma_f32_16x16x32_bf16 v[66:69], v[238:241], v[200:203], v[66:69]
	s_mov_b32 m0, s2
	v_lshl_add_u64 v[248:249], v[164:165], 0, v[170:171]
	s_barrier
	ds_read_b128 v[152:155], v233 offset:16384
	ds_read_b128 v[156:159], v233 offset:17408
	ds_read_b128 v[160:163], v233 offset:18432
	ds_read_b128 v[184:187], v233 offset:19456
	ds_read_b128 v[188:191], v233 offset:20480
	ds_read_b128 v[192:195], v233 offset:21504
	ds_read_b128 v[196:199], v233 offset:22528
	ds_read_b128 v[200:203], v233 offset:23552
	global_load_lds_dwordx4 v[248:249], off
	v_lshl_add_u64 v[250:251], v[164:165], 0, v[166:167]
	s_mov_b32 m0, s3
	s_nop 0
	global_load_lds_dwordx4 v[250:251], off
	s_barrier
	s_waitcnt lgkmcnt(0)
	s_waitcnt lgkmcnt(0)
	v_mfma_f32_16x16x32_bf16 v[62:65], v[136:139], v[152:155], v[62:65]
	v_mfma_f32_16x16x32_bf16 v[58:61], v[144:147], v[152:155], v[58:61]
	v_mfma_f32_16x16x32_bf16 v[46:49], v[136:139], v[160:163], v[46:49]
	v_mfma_f32_16x16x32_bf16 v[42:45], v[144:147], v[160:163], v[42:45]
	v_mfma_f32_16x16x32_bf16 v[30:33], v[136:139], v[188:191], v[30:33]
	v_mfma_f32_16x16x32_bf16 v[26:29], v[144:147], v[188:191], v[26:29]
	v_mfma_f32_16x16x32_bf16 v[14:17], v[136:139], v[196:199], v[14:17]
	v_mfma_f32_16x16x32_bf16 v[10:13], v[144:147], v[196:199], v[10:13]
	v_mfma_f32_16x16x32_bf16 v[62:65], v[140:143], v[156:159], v[62:65]
	v_mfma_f32_16x16x32_bf16 v[58:61], v[148:151], v[156:159], v[58:61]
	v_mfma_f32_16x16x32_bf16 v[46:49], v[140:143], v[184:187], v[46:49]
	v_mfma_f32_16x16x32_bf16 v[42:45], v[148:151], v[184:187], v[42:45]
	v_mfma_f32_16x16x32_bf16 v[30:33], v[140:143], v[192:195], v[30:33]
	v_mfma_f32_16x16x32_bf16 v[26:29], v[148:151], v[192:195], v[26:29]
	v_mfma_f32_16x16x32_bf16 v[14:17], v[140:143], v[200:203], v[14:17]
	v_mfma_f32_16x16x32_bf16 v[10:13], v[148:151], v[200:203], v[10:13]
	s_barrier
; #define PG8_STAGE(bufoff, gbase, voff) do { _Pragma("unroll") for (int _i = 0; _i < 2; ++_i) \
;         __builtin_amdgcn_global_load_lds((const unsigned*)((const char*)(gbase) + (voff)[_i]), (LAS unsigned*)(lds + (bufoff) + ldsw + _i * 8192), 16, 0, 0); } while (0)
; #define PG8_LDA(dst, b, h) do { _Pragma("unroll") for (int m = 0; m < 4; ++m) _Pragma("unroll") for (int k = 0; k < 2; ++k) dst[m][k] = *(const LAS bf16x8*)(lds + PG8_SA(b, h) + aoff + m * 2048 + k * 1024); } while (0)
; #define PG8_LDB(dst, b, h) do { _Pragma("unroll") for (int n = 0; n < 2; ++n) _Pragma("unroll") for (int k = 0; k < 2; ++k) dst[n][k] = *(const LAS bf16x8*)(lds + PG8_SB(b, h) + boff + n * 2048 + k * 1024); } while (0)
; #define PG8_MMA(ai, bj, At, Bt) do { __builtin_amdgcn_s_setprio(1); _Pragma("unroll") for (int m = 0; m < 4; ++m) _Pragma("unroll") for (int n = 0; n < 2; ++n) _Pragma("unroll") for (int k = 0; k < 2; ++k) \
;         acc[ai][bj][m][n] = __builtin_amdgcn_mfma_f32_16x16x32_bf16(Bt[n][k], At[m][k], acc[ai][bj][m][n], 0, 0, 0); __builtin_amdgcn_s_setprio(0); } while (0)
; #define PG8_WAIT_V(n) asm volatile("s_waitcnt vmcnt(" #n ")" ::: "memory")
; #define PG8_WAIT_L(n) asm volatile("s_waitcnt lgkmcnt(" #n ")" ::: "memory")
; #define PG8_BAR __builtin_amdgcn_s_barrier()
; #define PG8_SCHED __builtin_amdgcn_sched_barrier(0)
; __device__ __forceinline__ void gemm_phase(LAS unsigned char* lds, const GemmD& g) {
;     ...
;             PG8_STAGE(PG8_SB(0, 1), b2 + hstep, voffB);
;             PG8_WAIT_V(6); PG8_BAR; PG8_MMA(1, 1, At, B1); PG8_BAR;
;             PG8_LDB(B0, 1, 0); PG8_SCHED; PG8_LDA(At, 1, 0); PG8_STAGE(PG8_SA(0, 1), a2 + hstep, voffA);
;             PG8_WAIT_L(8); PG8_BAR; PG8_WAIT_L(0); PG8_MMA(0, 0, At, B0); PG8_BAR; PG8_SCHED;
;             PG8_LDB(B1, 1, 1); PG8_STAGE(PG8_SB(1, 0), b3, voffB);
;             PG8_BAR; PG8_WAIT_L(0); PG8_MMA(0, 1, At, B1); PG8_BAR;
;             PG8_LDA(At, 1, 1); PG8_STAGE(PG8_SA(1, 0), a3, voffA);
	v_lshl_add_u64 v[136:137], v[242:243], 0, s[72:73]
	s_add_i32 s4, s4, s87
	v_lshl_add_u64 v[242:243], v[136:137], 0, v[172:173]
	s_mov_b32 m0, s4
	v_lshl_add_u64 v[252:253], v[136:137], 0, v[168:169]
	global_load_lds_dwordx4 v[242:243], off
	s_add_i32 m0, s4, 0x2000
	s_nop 0
	global_load_lds_dwordx4 v[252:253], off
	s_waitcnt vmcnt(6)
	s_barrier
	v_mfma_f32_16x16x32_bf16 v[54:57], v[204:207], v[152:155], v[54:57]
	v_mfma_f32_16x16x32_bf16 v[50:53], v[234:237], v[152:155], v[50:53]
	v_mfma_f32_16x16x32_bf16 v[38:41], v[204:207], v[160:163], v[38:41]
	v_mfma_f32_16x16x32_bf16 v[34:37], v[234:237], v[160:163], v[34:37]
	v_mfma_f32_16x16x32_bf16 v[22:25], v[204:207], v[188:191], v[22:25]
	v_mfma_f32_16x16x32_bf16 v[18:21], v[234:237], v[188:191], v[18:21]
	v_mfma_f32_16x16x32_bf16 v[6:9], v[204:207], v[196:199], v[6:9]
	v_mfma_f32_16x16x32_bf16 v[2:5], v[234:237], v[196:199], v[2:5]
	v_mfma_f32_16x16x32_bf16 v[54:57], v[208:211], v[156:159], v[54:57]
	v_mfma_f32_16x16x32_bf16 v[50:53], v[238:241], v[156:159], v[50:53]
	v_mfma_f32_16x16x32_bf16 v[38:41], v[208:211], v[184:187], v[38:41]
	v_mfma_f32_16x16x32_bf16 v[34:37], v[238:241], v[184:187], v[34:37]
	v_mfma_f32_16x16x32_bf16 v[22:25], v[208:211], v[192:195], v[22:25]
	v_mfma_f32_16x16x32_bf16 v[18:21], v[238:241], v[192:195], v[18:21]
	v_mfma_f32_16x16x32_bf16 v[6:9], v[208:211], v[200:203], v[6:9]
	v_mfma_f32_16x16x32_bf16 v[2:5], v[238:241], v[200:203], v[2:5]
	s_add_i32 s4, 0, 0x18000
	v_add_u32_e32 v148, s4, v229
	s_barrier
	ds_read_b128 v[136:139], v148
	ds_read_b128 v[140:143], v148 offset:1024
	ds_read_b128 v[144:147], v148 offset:2048
	ds_read_b128 v[148:151], v148 offset:3072
	v_lshl_add_u64 v[164:165], v[164:165], 0, s[72:73]
	s_mov_b32 m0, s64
	v_lshl_add_u64 v[204:205], v[164:165], 0, v[170:171]
	ds_read_b128 v[152:155], v233 offset:32768
	ds_read_b128 v[156:159], v233 offset:33792
	ds_read_b128 v[160:163], v233 offset:34816
	ds_read_b128 v[184:187], v233 offset:35840
	ds_read_b128 v[188:191], v233 offset:36864
	ds_read_b128 v[192:195], v233 offset:37888
	ds_read_b128 v[196:199], v233 offset:38912
	ds_read_b128 v[200:203], v233 offset:39936
	global_load_lds_dwordx4 v[204:205], off
	v_lshl_add_u64 v[164:165], v[164:165], 0, v[166:167]
	s_mov_b32 m0, s65
	s_nop 0
	global_load_lds_dwordx4 v[164:165], off
	s_waitcnt lgkmcnt(8)
	s_barrier
	s_waitcnt lgkmcnt(0)
	s_waitcnt lgkmcnt(0)
	v_mfma_f32_16x16x32_bf16 v[126:129], v[136:139], v[152:155], v[126:129]
	v_mfma_f32_16x16x32_bf16 v[122:125], v[144:147], v[152:155], v[122:125]
	v_mfma_f32_16x16x32_bf16 v[110:113], v[136:139], v[160:163], v[110:113]
	v_mfma_f32_16x16x32_bf16 v[106:109], v[144:147], v[160:163], v[106:109]
	v_mfma_f32_16x16x32_bf16 v[94:97], v[136:139], v[188:191], v[94:97]
	v_mfma_f32_16x16x32_bf16 v[90:93], v[144:147], v[188:191], v[90:93]
	v_mfma_f32_16x16x32_bf16 v[78:81], v[136:139], v[196:199], v[78:81]
	v_mfma_f32_16x16x32_bf16 v[74:77], v[144:147], v[196:199], v[74:77]
	v_mfma_f32_16x16x32_bf16 v[126:129], v[140:143], v[156:159], v[126:129]
	v_mfma_f32_16x16x32_bf16 v[122:125], v[148:151], v[156:159], v[122:125]
	v_mfma_f32_16x16x32_bf16 v[110:113], v[140:143], v[184:187], v[110:113]
	v_mfma_f32_16x16x32_bf16 v[106:109], v[148:151], v[184:187], v[106:109]
	v_mfma_f32_16x16x32_bf16 v[94:97], v[140:143], v[192:195], v[94:97]
	v_mfma_f32_16x16x32_bf16 v[90:93], v[148:151], v[192:195], v[90:93]
	v_mfma_f32_16x16x32_bf16 v[78:81], v[140:143], v[200:203], v[78:81]
	v_mfma_f32_16x16x32_bf16 v[74:77], v[148:151], v[200:203], v[74:77]
	s_barrier
	s_add_i32 s6, 0, 0x1c000
	v_add_u32_e32 v164, s6, v229
	s_add_i32 s4, s4, s87
	ds_read_b128 v[204:207], v164
	ds_read_b128 v[208:211], v164 offset:1024
	ds_read_b128 v[234:237], v164 offset:2048
	ds_read_b128 v[238:241], v164 offset:3072
	v_lshl_add_u64 v[164:165], v[244:245], 0, s[44:45]
	s_mov_b32 m0, s4
	s_nop 0
	global_load_lds_dwordx4 v[164:165], off
	v_lshl_add_u64 v[164:165], v[246:247], 0, s[44:45]
	s_add_i32 m0, s4, 0x2000
	s_nop 0
	global_load_lds_dwordx4 v[164:165], off
	s_barrier
; #define PG8_STAGE(bufoff, gbase, voff) do { _Pragma("unroll") for (int _i = 0; _i < 2; ++_i) \
;         __builtin_amdgcn_global_load_lds((const unsigned*)((const char*)(gbase) + (voff)[_i]), (LAS unsigned*)(lds + (bufoff) + ldsw + _i * 8192), 16, 0, 0); } while (0)
; #define PG8_LDA(dst, b, h) do { _Pragma("unroll") for (int m = 0; m < 4; ++m) _Pragma("unroll") for (int k = 0; k < 2; ++k) dst[m][k] = *(const LAS bf16x8*)(lds + PG8_SA(b, h) + aoff + m * 2048 + k * 1024); } while (0)
; #define PG8_LDB(dst, b, h) do { _Pragma("unroll") for (int n = 0; n < 2; ++n) _Pragma("unroll") for (int k = 0; k < 2; ++k) dst[n][k] = *(const LAS bf16x8*)(lds + PG8_SB(b, h) + boff + n * 2048 + k * 1024); } while (0)
; #define PG8_MMA(ai, bj, At, Bt) do { __builtin_amdgcn_s_setprio(1); _Pragma("unroll") for (int m = 0; m < 4; ++m) _Pragma("unroll") for (int n = 0; n < 2; ++n) _Pragma("unroll") for (int k = 0; k < 2; ++k) \
;         acc[ai][bj][m][n] = __builtin_amdgcn_mfma_f32_16x16x32_bf16(Bt[n][k], At[m][k], acc[ai][bj][m][n], 0, 0, 0); __builtin_amdgcn_s_setprio(0); } while (0)
; #define PG8_WAIT_V(n) asm volatile("s_waitcnt vmcnt(" #n ")" ::: "memory")
; #define PG8_WAIT_L(n) asm volatile("s_waitcnt lgkmcnt(" #n ")" ::: "memory")
; #define PG8_BAR __builtin_amdgcn_s_barrier()
; #define PG8_SCHED __builtin_amdgcn_sched_barrier(0)
; __device__ __forceinline__ void gemm_phase(LAS unsigned char* lds, const GemmD& g) {
;     ...
;             PG8_LDB(B1, 1, 1); PG8_STAGE(PG8_SB(1, 0), b3, voffB);
;             PG8_BAR; PG8_WAIT_L(0); PG8_MMA(0, 1, At, B1); PG8_BAR;
;             PG8_LDA(At, 1, 1); PG8_STAGE(PG8_SA(1, 0), a3, voffA);
;             PG8_BAR; PG8_WAIT_L(0); PG8_MMA(1, 0, At, B0); PG8_BAR; PG8_SCHED;
;             PG8_STAGE(PG8_SB(1, 1), b3 + hstep, voffB);
;             PG8_WAIT_V(6); PG8_BAR; PG8_MMA(1, 1, At, B1); PG8_BAR;
;         }
	s_waitcnt lgkmcnt(0)
	s_waitcnt lgkmcnt(0)
	v_mfma_f32_16x16x32_bf16 v[118:121], v[204:207], v[152:155], v[118:121]
	v_mfma_f32_16x16x32_bf16 v[114:117], v[234:237], v[152:155], v[114:117]
	v_mfma_f32_16x16x32_bf16 v[102:105], v[204:207], v[160:163], v[102:105]
	v_mfma_f32_16x16x32_bf16 v[98:101], v[234:237], v[160:163], v[98:101]
	v_mfma_f32_16x16x32_bf16 v[86:89], v[204:207], v[188:191], v[86:89]
	v_mfma_f32_16x16x32_bf16 v[82:85], v[234:237], v[188:191], v[82:85]
	v_mfma_f32_16x16x32_bf16 v[70:73], v[204:207], v[196:199], v[70:73]
	v_mfma_f32_16x16x32_bf16 v[66:69], v[234:237], v[196:199], v[66:69]
	v_mfma_f32_16x16x32_bf16 v[118:121], v[208:211], v[156:159], v[118:121]
	v_mfma_f32_16x16x32_bf16 v[114:117], v[238:241], v[156:159], v[114:117]
	v_mfma_f32_16x16x32_bf16 v[102:105], v[208:211], v[184:187], v[102:105]
	v_mfma_f32_16x16x32_bf16 v[98:101], v[238:241], v[184:187], v[98:101]
	v_mfma_f32_16x16x32_bf16 v[86:89], v[208:211], v[192:195], v[86:89]
	v_mfma_f32_16x16x32_bf16 v[82:85], v[238:241], v[192:195], v[82:85]
	v_mfma_f32_16x16x32_bf16 v[70:73], v[208:211], v[200:203], v[70:73]
	v_mfma_f32_16x16x32_bf16 v[66:69], v[238:241], v[200:203], v[66:69]
	s_mov_b32 m0, s28
	v_lshl_add_u64 v[164:165], v[248:249], 0, s[44:45]
	s_barrier
	ds_read_b128 v[152:155], v233 offset:49152
	ds_read_b128 v[156:159], v233 offset:50176
	ds_read_b128 v[160:163], v233 offset:51200
	ds_read_b128 v[184:187], v233 offset:52224
	ds_read_b128 v[188:191], v233 offset:53248
	ds_read_b128 v[192:195], v233 offset:54272
	ds_read_b128 v[196:199], v233 offset:55296
	ds_read_b128 v[200:203], v233 offset:56320
	global_load_lds_dwordx4 v[164:165], off
	v_lshl_add_u64 v[164:165], v[250:251], 0, s[44:45]
	s_mov_b32 m0, s29
	s_nop 0
	global_load_lds_dwordx4 v[164:165], off
	s_barrier
	s_waitcnt lgkmcnt(0)
	s_waitcnt lgkmcnt(0)
	v_mfma_f32_16x16x32_bf16 v[62:65], v[136:139], v[152:155], v[62:65]
	v_mfma_f32_16x16x32_bf16 v[58:61], v[144:147], v[152:155], v[58:61]
	v_mfma_f32_16x16x32_bf16 v[46:49], v[136:139], v[160:163], v[46:49]
	v_mfma_f32_16x16x32_bf16 v[42:45], v[144:147], v[160:163], v[42:45]
	v_mfma_f32_16x16x32_bf16 v[30:33], v[136:139], v[188:191], v[30:33]
	v_mfma_f32_16x16x32_bf16 v[26:29], v[144:147], v[188:191], v[26:29]
	v_mfma_f32_16x16x32_bf16 v[14:17], v[136:139], v[196:199], v[14:17]
	v_mfma_f32_16x16x32_bf16 v[10:13], v[144:147], v[196:199], v[10:13]
	v_mfma_f32_16x16x32_bf16 v[62:65], v[140:143], v[156:159], v[62:65]
	v_mfma_f32_16x16x32_bf16 v[58:61], v[148:151], v[156:159], v[58:61]
	v_mfma_f32_16x16x32_bf16 v[46:49], v[140:143], v[184:187], v[46:49]
	v_mfma_f32_16x16x32_bf16 v[42:45], v[148:151], v[184:187], v[42:45]
	v_mfma_f32_16x16x32_bf16 v[30:33], v[140:143], v[192:195], v[30:33]
	v_mfma_f32_16x16x32_bf16 v[26:29], v[148:151], v[192:195], v[26:29]
	v_mfma_f32_16x16x32_bf16 v[14:17], v[140:143], v[200:203], v[14:17]
	v_mfma_f32_16x16x32_bf16 v[10:13], v[148:151], v[200:203], v[10:13]
	s_barrier
	s_add_i32 s4, s6, s87
	v_lshl_add_u64 v[136:137], v[242:243], 0, s[44:45]
	s_mov_b32 m0, s4
	s_nop 0
	global_load_lds_dwordx4 v[136:137], off
	v_lshl_add_u64 v[136:137], v[252:253], 0, s[44:45]
	s_add_i32 m0, s4, 0x2000
	s_nop 0
	global_load_lds_dwordx4 v[136:137], off
	s_waitcnt vmcnt(6)
	s_barrier
	v_mfma_f32_16x16x32_bf16 v[54:57], v[204:207], v[152:155], v[54:57]
	v_mfma_f32_16x16x32_bf16 v[50:53], v[234:237], v[152:155], v[50:53]
	v_mfma_f32_16x16x32_bf16 v[38:41], v[204:207], v[160:163], v[38:41]
	v_mfma_f32_16x16x32_bf16 v[34:37], v[234:237], v[160:163], v[34:37]
	v_mfma_f32_16x16x32_bf16 v[22:25], v[204:207], v[188:191], v[22:25]
	v_mfma_f32_16x16x32_bf16 v[18:21], v[234:237], v[188:191], v[18:21]
	v_mfma_f32_16x16x32_bf16 v[6:9], v[204:207], v[196:199], v[6:9]
	v_mfma_f32_16x16x32_bf16 v[2:5], v[234:237], v[196:199], v[2:5]
	v_mfma_f32_16x16x32_bf16 v[54:57], v[208:211], v[156:159], v[54:57]
	v_mfma_f32_16x16x32_bf16 v[50:53], v[238:241], v[156:159], v[50:53]
	v_mfma_f32_16x16x32_bf16 v[38:41], v[208:211], v[184:187], v[38:41]
	v_mfma_f32_16x16x32_bf16 v[34:37], v[238:241], v[184:187], v[34:37]
	v_mfma_f32_16x16x32_bf16 v[22:25], v[208:211], v[192:195], v[22:25]
	v_mfma_f32_16x16x32_bf16 v[18:21], v[238:241], v[192:195], v[18:21]
	v_mfma_f32_16x16x32_bf16 v[6:9], v[208:211], v[200:203], v[6:9]
	v_mfma_f32_16x16x32_bf16 v[2:5], v[238:241], v[200:203], v[2:5]
	v_cmp_ge_u32_e32 vcc, s5, v134
	v_lshl_add_u64 v[130:131], v[130:131], 0, s[46:47]
	v_lshl_add_u64 v[132:133], v[132:133], 0, s[46:47]
	s_mov_b32 s4, s5
	s_barrier
	s_cbranch_vccz .LBB0_145
	v_lshl_add_u32 v184, s56, 8, v228
	s_cmp_lt_i32 s66, 0
	s_mov_b64 s[4:5], -1
	s_cbranch_scc0 .LBB0_704
